# P3b CU-partner stagger: workgroups >= 256 run their GDN p4 items first and the HG scan last, so a latency-bound scan overlaps the partner's throughput-bound items
# speedup vs baseline: 1.0193x; 1.0150x over previous
.LBB0_984:
	s_or_b64 exec, exec, s[0:1]
	s_cmpk_gt_i32 s2, 0x57f
	s_barrier
	s_mov_b32 s96, 0
	s_cbranch_scc1 .LBB0_1029
	s_cmpk_lt_u32 s2, 0x100
	s_cbranch_scc1 .Lp3b_scan
	s_mov_b32 s96, 1
	s_branch .LBB0_1029
.Lp3b_scan:
	s_add_u32 s4, s20, 0x19448000
	s_addc_u32 s5, s21, 0
	s_add_u32 s6, s20, 0x1d648000
	s_addc_u32 s7, s21, 0
	s_add_u32 s29, s50, 0x84da000
	s_addc_u32 s36, s51, 0
	s_add_u32 s37, s20, 0x11048000
	s_addc_u32 s38, s21, 0
	s_add_u32 s39, s20, 0x13148000
	s_addc_u32 s42, s21, 0
	s_add_u32 s43, s20, 0x17348000
	s_addc_u32 s46, s21, 0
	s_add_u32 s47, s50, 0x82da000
	s_addc_u32 s56, s51, 0
	s_add_u32 s57, s50, 0x8192000
	s_addc_u32 s62, s51, 0
	s_add_u32 s63, s20, 0x194c0004
	s_addc_u32 s64, s21, 0
	s_mov_b32 s9, 0
	s_waitcnt vmcnt(23)
	v_mov_b32_e32 v73, 0
	s_movk_i32 s65, 0x840
	s_movk_i32 s66, 0x210
	s_movk_i32 s67, 0x3c0
	s_mov_b64 s[10:11], 0x80000
	s_mov_b32 s68, s2
	s_mov_b32 s69, s2
	s_branch .LBB0_988

.Lp3b_after_scan:
	s_cmp_eq_u32 s96, 2
	s_cbranch_scc1 .LBB0_1032

.LBB0_1031:
	v_cmp_lt_i32_e32 vcc, v21, v22
	v_mov_b32_e32 v0, v181
	s_ashr_i32 s0, s39, 3
	v_cndmask_b32_e32 v2, v20, v21, vcc
	v_cmp_lt_i32_e32 vcc, v23, v22
	s_waitcnt vmcnt(28)
	v_lshlrev_b32_e32 v33, 2, v2
	v_ashrrev_i32_e32 v2, 6, v0
	v_cndmask_b32_e32 v3, v20, v23, vcc
	v_cmp_lt_i32_e32 vcc, v24, v22
	v_lshlrev_b32_e32 v32, 2, v3
	v_and_b32_e32 v3, 63, v0
	v_cndmask_b32_e32 v4, v20, v24, vcc
	v_cmp_lt_i32_e32 vcc, v25, v22
	v_lshlrev_b32_e32 v31, 2, v4
	v_and_b32_e32 v4, 15, v0
	v_cndmask_b32_e32 v5, v20, v25, vcc
	v_lshlrev_b32_e32 v30, 2, v5
	v_lshrrev_b32_e32 v0, 2, v0
	v_lshlrev_b32_e32 v5, 4, v2
	s_lshl_b32 s1, s39, 7
	v_and_b32_e32 v6, 12, v0
	v_lshlrev_b32_e32 v7, 2, v3
	v_lshlrev_b32_e32 v12, 5, v3
	v_lshl_add_u32 v3, s0, 6, v5
	s_and_b32 s4, s39, 0xfffffc00
	s_and_b32 s8, s1, 0x380
	v_lshlrev_b32_e32 v8, 1, v4
	v_lshlrev_b32_e32 v0, 2, v4
	v_or_b32_e32 v5, v5, v4
	v_or_b32_e32 v4, v3, v6
	s_and_b32 s1, s0, 0x7f
	s_or_b32 s4, s8, s4
	global_load_dword v29, v0, s[40:41]
	global_load_dword v28, v0, s[40:41] offset:64
	global_load_dword v27, v0, s[40:41] offset:128
	global_load_dword v26, v0, s[40:41] offset:192
	v_lshlrev_b32_e32 v0, 1, v6
	v_lshlrev_b32_e32 v6, 6, v5
	v_ashrrev_i32_e32 v5, 31, v4
	s_or_b32 s4, s4, s1
	s_waitcnt vmcnt(28)
	v_lshlrev_b64 v[66:67], 13, v[4:5]
	s_ashr_i32 s5, s4, 31
	v_or_b32_e32 v14, 1, v4
	v_or_b32_e32 v16, 2, v4
	v_or_b32_e32 v18, 3, v4
	v_lshl_add_u64 v[4:5], s[20:21], 0, v[66:67]
	s_lshl_b64 s[0:1], s[4:5], 13
	v_lshl_add_u64 v[4:5], v[4:5], 0, s[8:9]
	s_add_u32 s4, s50, s0
	v_lshl_add_u64 v[50:51], v[4:5], 0, v[8:9]
	s_addc_u32 s5, s51, s1
	v_add_co_u32_e32 v52, vcc, s36, v50
	s_add_u32 s6, s17, s0
	s_nop 0
	v_addc_co_u32_e32 v53, vcc, 0, v51, vcc
	v_lshl_or_b32 v2, v2, 10, v7
	v_ashrrev_i32_e32 v7, 31, v6
	s_addc_u32 s7, s29, s1
	v_add_co_u32_e32 v54, vcc, s37, v50
	v_mov_b32_e32 v1, v9
	v_ashrrev_i32_e32 v3, 31, v2
	v_lshl_add_u64 v[6:7], v[6:7], 1, s[4:5]
	s_add_u32 s0, s15, s0
	v_addc_co_u32_e32 v55, vcc, 0, v51, vcc
	v_mov_b32_e32 v13, v9
	v_lshl_add_u64 v[34:35], v[6:7], 0, v[0:1]
	v_lshl_add_u64 v[36:37], v[2:3], 1, s[6:7]
	s_addc_u32 s1, s16, s1
	v_add_co_u32_e32 v56, vcc, s38, v50
	global_load_dwordx2 v[4:5], v[34:35], off
	global_load_dwordx2 v[6:7], v[34:35], off offset:32
	global_load_dwordx2 v[0:1], v[34:35], off offset:64
	global_load_dwordx2 v[2:3], v[34:35], off offset:96
	global_load_dwordx2 v[68:69], v[36:37], off
	global_load_dwordx2 v[72:73], v[36:37], off offset:512
	global_load_dwordx2 v[76:77], v[36:37], off offset:1024
	global_load_dwordx2 v[80:81], v[36:37], off offset:1536
	v_addc_co_u32_e32 v57, vcc, 0, v51, vcc
	global_load_ushort v82, v[50:51], off offset:3072
	global_load_ushort v83, v[50:51], off offset:3104
	global_load_ushort v84, v[50:51], off offset:3136
	global_load_ushort v85, v[50:51], off offset:3168
	global_load_dwordx4 v[34:37], v12, s[0:1]
	global_load_dwordx4 v[38:41], v12, s[0:1] offset:2048
	global_load_dwordx4 v[42:45], v12, s[0:1] offset:16
	global_load_dwordx4 v[46:49], v12, s[0:1] offset:2064
	global_load_ushort v86, v[52:53], off offset:3072
	global_load_ushort v87, v[54:55], off offset:3072
	global_load_ushort v88, v[56:57], off offset:3072
	global_load_ushort v89, v[52:53], off offset:3104
	global_load_ushort v90, v[54:55], off offset:3104
	global_load_ushort v91, v[56:57], off offset:3104
	global_load_ushort v92, v[52:53], off offset:3136
	global_load_ushort v93, v[54:55], off offset:3136
	global_load_ushort v94, v[56:57], off offset:3136
	global_load_ushort v95, v[54:55], off offset:3168
	global_load_ushort v96, v[52:53], off offset:3168
	global_load_ushort v97, v[56:57], off offset:3168
	v_lshl_add_u64 v[12:13], s[0:1], 0, v[12:13]
	v_lshl_add_u64 v[70:71], v[12:13], 0, s[10:11]
	s_waitcnt vmcnt(55)
	v_lshl_add_u64 v[74:75], v[12:13], 0, s[12:13]
	v_add_co_u32_e32 v12, vcc, s34, v12
	s_add_u32 s0, s20, s8
	s_nop 0
	v_addc_co_u32_e32 v13, vcc, 0, v13, vcc
	global_load_dwordx4 v[50:53], v[12:13], off
	global_load_dwordx4 v[54:57], v[12:13], off offset:2048
	global_load_dwordx4 v[58:61], v[70:71], off offset:16
	global_load_dwordx4 v[62:65], v[74:75], off offset:16
	s_addc_u32 s1, s21, 0
	v_and_b32_e32 v12, 0xffe00000, v66
	v_lshrrev_b32_e32 v13, 5, v66
	v_and_b32_e32 v13, 0xe000, v13
	v_lshrrev_b32_e32 v14, 7, v66
	v_and_b32_e32 v14, 0x7c0, v14
	v_lshrrev_b32_e32 v15, 10, v66
	v_and_b32_e32 v15, 32, v15
	v_and_b32_e32 v16, 30, v8
	v_or3_b32 v12, v12, v13, v14
	v_or3_b32 v12, v12, v15, v16
	s_lshl_b32 s8, s8, 10
	v_add_u32_e32 v12, s8, v12
	v_xor_b32_e32 v16, 16, v12
	v_add_u32_e32 v14, 64, v12
	v_add_u32_e32 v18, 0xc0, v16
	v_add_u32_e32 v16, 0x80, v16
	v_xor_b32_e32 v13, 32, v12
	v_xor_b32_e32 v15, 32, v14
	v_xor_b32_e32 v17, 32, v16
	v_xor_b32_e32 v19, 32, v18
	s_add_i32 s39, s39, s22
	s_cmpk_lt_i32 s39, 0x1000
	s_waitcnt vmcnt(23)
	v_lshlrev_b32_e32 v8, 16, v82
	s_waitcnt vmcnt(22)
	v_lshlrev_b32_e32 v98, 16, v83
	s_waitcnt vmcnt(21)
	v_lshlrev_b32_e32 v99, 16, v84
	s_waitcnt vmcnt(20)
	v_lshlrev_b32_e32 v100, 16, v85
	s_waitcnt vmcnt(19)
	v_mov_b32_e32 v82, v34
	v_mov_b32_e32 v83, v35
	s_waitcnt vmcnt(18)
	v_mov_b32_e32 v84, v38
	v_mov_b32_e32 v85, v39
	s_waitcnt vmcnt(17)
	v_mov_b32_e32 v34, v42
	v_mov_b32_e32 v35, v43
	v_mul_f32_e32 v42, 0xbfb8aa3b, v8
	v_mul_f32_e32 v43, 0xbfb8aa3b, v98
	v_mov_b32_e32 v38, v36
	v_mov_b32_e32 v39, v37
	v_lshlrev_b32_e32 v66, 16, v68
	v_and_b32_e32 v67, 0xffff0000, v68
	v_lshlrev_b32_e32 v68, 16, v69
	v_and_b32_e32 v69, 0xffff0000, v69
	v_lshlrev_b32_e32 v70, 16, v72
	v_and_b32_e32 v71, 0xffff0000, v72
	v_lshlrev_b32_e32 v72, 16, v73
	v_and_b32_e32 v73, 0xffff0000, v73
	s_waitcnt vmcnt(16)
	v_mov_b32_e32 v36, v46
	v_mov_b32_e32 v37, v47
	v_mov_b32_e32 v46, v44
	v_mov_b32_e32 v47, v45
	v_exp_f32_e32 v103, v42
	v_exp_f32_e32 v107, v43
	v_mfma_f32_16x16x32_bf16 v[42:45], v[4:7], v[82:85], v[66:69]
	v_lshlrev_b32_e32 v74, 16, v76
	v_and_b32_e32 v75, 0xffff0000, v76
	v_lshlrev_b32_e32 v76, 16, v77
	v_and_b32_e32 v77, 0xffff0000, v77
	v_lshlrev_b32_e32 v78, 16, v80
	v_and_b32_e32 v79, 0xffff0000, v80
	v_lshlrev_b32_e32 v80, 16, v81
	v_and_b32_e32 v81, 0xffff0000, v81
	s_waitcnt vmcnt(15)
	v_lshlrev_b32_e32 v86, 16, v86
	s_waitcnt vmcnt(14)
	v_lshlrev_b32_e32 v87, 16, v87
	v_mul_f32_e32 v101, 0xbfb8aa3b, v99
	v_mfma_f32_16x16x32_bf16 v[38:41], v[4:7], v[38:41], v[70:73]
	s_waitcnt vmcnt(8)
	v_lshlrev_b32_e32 v93, 16, v93
	s_waitcnt vmcnt(7)
	v_lshlrev_b32_e32 v94, 16, v94
	v_mul_f32_e32 v104, 0xbfb8aa3b, v86
	v_mul_f32_e32 v105, 0xbfb8aa3b, v87
	v_exp_f32_e32 v67, v101
	v_mfma_f32_16x16x32_bf16 v[34:37], v[4:7], v[34:37], v[74:77]
	v_lshlrev_b32_e32 v88, 16, v88
	v_lshlrev_b32_e32 v89, 16, v89
	v_lshlrev_b32_e32 v90, 16, v90
	v_mfma_f32_16x16x32_bf16 v[4:7], v[4:7], v[46:49], v[78:81]
	v_lshlrev_b32_e32 v92, 16, v92
	s_waitcnt vmcnt(5)
	v_lshlrev_b32_e32 v96, 16, v96
	v_lshlrev_b32_e32 v95, 16, v95
	v_mul_f32_e32 v69, 0xbfb8aa3b, v93
	v_mul_f32_e32 v70, 0xbfb8aa3b, v94
	s_waitcnt vmcnt(3)
	v_mov_b32_e32 v46, v50
	v_mov_b32_e32 v47, v51
	s_waitcnt vmcnt(2)
	v_mov_b32_e32 v48, v54
	v_mov_b32_e32 v49, v55
	s_waitcnt vmcnt(1)
	v_mov_b32_e32 v50, v58
	v_mov_b32_e32 v51, v59
	v_exp_f32_e32 v58, v104
	v_exp_f32_e32 v59, v105
	v_lshlrev_b32_e32 v91, 16, v91
	v_mul_f32_e32 v102, 0xbfb8aa3b, v100
	v_lshlrev_b32_e32 v97, 16, v97
	v_mul_f32_e32 v106, 0xbfb8aa3b, v88
	v_mul_f32_e32 v108, 0xbfb8aa3b, v89
	v_mul_f32_e32 v109, 0xbfb8aa3b, v90
	v_mul_f32_e32 v68, 0xbfb8aa3b, v92
	v_mul_f32_e32 v72, 0xbfb8aa3b, v96
	v_mul_f32_e32 v73, 0xbfb8aa3b, v95
	v_mov_b32_e32 v54, v52
	v_mov_b32_e32 v55, v53
	v_mfma_f32_16x16x32_bf16 v[42:45], v[0:3], v[46:49], v[42:45]
	v_exp_f32_e32 v46, v69
	v_exp_f32_e32 v47, v70
	v_mul_f32_e32 v66, 0xbfb8aa3b, v91
	v_exp_f32_e32 v71, v102
	v_mul_f32_e32 v74, 0xbfb8aa3b, v97
	s_waitcnt vmcnt(0)
	v_mov_b32_e32 v52, v62
	v_mov_b32_e32 v53, v63
	v_mov_b32_e32 v62, v60
	v_mov_b32_e32 v63, v61
	v_exp_f32_e32 v60, v106
	v_exp_f32_e32 v61, v108
	v_exp_f32_e32 v75, v109
	v_exp_f32_e32 v68, v68
	v_exp_f32_e32 v48, v72
	v_mfma_f32_16x16x32_bf16 v[38:41], v[0:3], v[54:57], v[38:41]
	v_exp_f32_e32 v49, v73
	v_exp_f32_e32 v66, v66
	v_exp_f32_e32 v54, v74
	v_add_f32_e32 v55, 1.0, v103
	v_mfma_f32_16x16x32_bf16 v[34:37], v[0:3], v[50:53], v[34:37]
	v_add_f32_e32 v50, 1.0, v107
	v_add_f32_e32 v51, 1.0, v67
	v_add_f32_e32 v46, 1.0, v46
	v_mfma_f32_16x16x32_bf16 v[0:3], v[0:3], v[62:65], v[4:7]
	v_rcp_f32_e32 v62, v55
	v_add_f32_e32 v47, 1.0, v47
	v_add_f32_e32 v52, 1.0, v71
	v_add_f32_e32 v4, 1.0, v58
	v_add_f32_e32 v5, 1.0, v59
	v_rcp_f32_e32 v58, v50
	v_rcp_f32_e32 v59, v51
	v_add_f32_e32 v6, 1.0, v60
	v_add_f32_e32 v7, 1.0, v61
	v_add_f32_e32 v50, 1.0, v75
	v_add_f32_e32 v51, 1.0, v68
	v_add_f32_e32 v48, 1.0, v48
	v_add_f32_e32 v49, 1.0, v49
	v_rcp_f32_e32 v61, v4
	v_rcp_f32_e32 v63, v5
	v_rcp_f32_e32 v69, v46
	v_rcp_f32_e32 v70, v47
	v_mov_b32_e32 v4, v42
	v_mov_b32_e32 v5, v38
	v_mov_b32_e32 v46, v43
	v_mov_b32_e32 v47, v39
	v_add_f32_e32 v53, 1.0, v66
	v_rcp_f32_e32 v60, v52
	v_add_f32_e32 v52, 1.0, v54
	v_rcp_f32_e32 v64, v6
	v_rcp_f32_e32 v65, v7
	v_rcp_f32_e32 v66, v50
	v_rcp_f32_e32 v68, v51
	v_rcp_f32_e32 v71, v48
	v_rcp_f32_e32 v72, v49
	v_mov_b32_e32 v6, v34
	v_mov_b32_e32 v7, v0
	v_mov_b32_e32 v48, v35
	v_mov_b32_e32 v49, v1
	v_mov_b32_e32 v50, v44
	v_mov_b32_e32 v51, v40
	v_mov_b32_e32 v54, v45
	v_mov_b32_e32 v55, v41
	v_pk_mul_f32 v[4:5], v[4:5], v[4:5]
	v_pk_mul_f32 v[46:47], v[46:47], v[46:47]
	v_rcp_f32_e32 v67, v53
	v_rcp_f32_e32 v73, v52
	v_mov_b32_e32 v52, v36
	v_mov_b32_e32 v53, v2
	v_mov_b32_e32 v56, v37
	v_mov_b32_e32 v57, v3
	v_mul_f32_e32 v8, v62, v8
	v_mul_f32_e32 v62, v58, v98
	v_mul_f32_e32 v74, v59, v99
	v_pk_mul_f32 v[6:7], v[6:7], v[6:7]
	v_pk_mul_f32 v[48:49], v[48:49], v[48:49]
	v_pk_mul_f32 v[50:51], v[50:51], v[50:51]
	v_pk_mul_f32 v[54:55], v[54:55], v[54:55]
	v_mov_b32_e32 v58, v46
	v_mov_b32_e32 v59, v4
	v_mov_b32_e32 v4, v47
	v_pk_mul_f32 v[52:53], v[52:53], v[52:53]
	v_pk_mul_f32 v[56:57], v[56:57], v[56:57]
	v_mov_b32_e32 v46, v48
	v_mov_b32_e32 v47, v6
	v_mov_b32_e32 v6, v49
	v_mov_b32_e32 v48, v54
	v_mov_b32_e32 v49, v50
	v_mov_b32_e32 v50, v55
	v_pk_add_f32 v[4:5], v[58:59], v[4:5]
	v_mov_b32_e32 v54, v56
	v_mov_b32_e32 v55, v52
	v_pk_add_f32 v[48:49], v[48:49], v[50:51]
	v_pk_add_f32 v[4:5], v[4:5], v[46:47]
	v_mov_b32_e32 v52, v57
	v_pk_add_f32 v[46:47], v[48:49], v[54:55]
	v_pk_add_f32 v[4:5], v[4:5], v[6:7]
	v_pk_add_f32 v[6:7], v[46:47], v[52:53]
	ds_bpermute_b32 v47, v33, v5
	ds_bpermute_b32 v46, v33, v4
	ds_bpermute_b32 v49, v33, v7
	ds_bpermute_b32 v48, v33, v6
	v_mul_f32_e32 v60, v60, v100
	v_mul_f32_e32 v61, v61, v86
	s_waitcnt lgkmcnt(2)
	v_pk_add_f32 v[4:5], v[4:5], v[46:47]
	ds_bpermute_b32 v47, v32, v5
	s_waitcnt lgkmcnt(1)
	v_pk_add_f32 v[6:7], v[6:7], v[48:49]
	ds_bpermute_b32 v46, v32, v4
	ds_bpermute_b32 v33, v32, v7
	ds_bpermute_b32 v32, v32, v6
	v_mul_f32_e32 v63, v63, v87
	v_mul_f32_e32 v64, v64, v88
	s_waitcnt lgkmcnt(2)
	v_pk_add_f32 v[4:5], v[4:5], v[46:47]
	v_mul_f32_e32 v65, v65, v89
	s_waitcnt lgkmcnt(0)
	v_pk_add_f32 v[6:7], v[6:7], v[32:33]
	ds_bpermute_b32 v33, v31, v5
	ds_bpermute_b32 v32, v31, v4
	ds_bpermute_b32 v47, v31, v7
	ds_bpermute_b32 v46, v31, v6
	v_mul_f32_e32 v66, v66, v90
	v_mul_f32_e32 v67, v67, v91
	s_waitcnt lgkmcnt(2)
	v_pk_add_f32 v[4:5], v[4:5], v[32:33]
	ds_bpermute_b32 v33, v30, v5
	s_waitcnt lgkmcnt(1)
	v_pk_add_f32 v[6:7], v[6:7], v[46:47]
	ds_bpermute_b32 v32, v30, v4
	ds_bpermute_b32 v31, v30, v7
	ds_bpermute_b32 v30, v30, v6
	v_mul_f32_e32 v68, v68, v92
	v_mul_f32_e32 v69, v69, v93
	s_waitcnt lgkmcnt(2)
	v_pk_add_f32 v[4:5], v[4:5], v[32:33]
	v_mul_f32_e32 v70, v70, v94
	s_waitcnt lgkmcnt(0)
	v_pk_add_f32 v[6:7], v[6:7], v[30:31]
	v_pk_fma_f32 v[4:5], v[4:5], s[14:15], v[10:11] op_sel_hi:[1,0,0]
	v_pk_fma_f32 v[6:7], v[6:7], s[14:15], v[10:11] op_sel_hi:[1,0,0]
	v_mul_f32_e32 v30, 0x4b800000, v5
	v_cmp_gt_f32_e64 s[6:7], s35, v5
	v_mul_f32_e32 v31, 0x4b800000, v4
	v_cmp_gt_f32_e32 vcc, s35, v4
	v_mul_f32_e32 v32, 0x4b800000, v7
	v_mul_f32_e32 v33, 0x4b800000, v6
	v_cmp_gt_f32_e64 s[0:1], s35, v6
	v_cmp_gt_f32_e64 s[4:5], s35, v7
	v_cndmask_b32_e64 v5, v5, v30, s[6:7]
	v_cndmask_b32_e32 v4, v4, v31, vcc
	v_cndmask_b32_e64 v7, v7, v32, s[4:5]
	v_cndmask_b32_e64 v6, v6, v33, s[0:1]
	v_rsq_f32_e32 v5, v5
	v_rsq_f32_e32 v4, v4
	v_rsq_f32_e32 v7, v7
	v_rsq_f32_e32 v6, v6
	v_mul_f32_e32 v30, 0x45800000, v5
	v_mul_f32_e32 v31, 0x45800000, v4
	v_mul_f32_e32 v32, 0x45800000, v7
	v_mul_f32_e32 v33, 0x45800000, v6
	v_cndmask_b32_e64 v5, v5, v30, s[6:7]
	v_cndmask_b32_e32 v4, v4, v31, vcc
	v_cndmask_b32_e64 v7, v7, v32, s[4:5]
	v_cndmask_b32_e64 v6, v6, v33, s[0:1]
	v_mul_f32_e32 v30, v42, v5
	v_mul_f32_e32 v31, v43, v4
	v_mul_f32_e32 v32, v44, v7
	v_mul_f32_e32 v33, v45, v6
	v_mul_f32_e32 v38, v38, v5
	v_mul_f32_e32 v39, v39, v4
	v_mul_f32_e32 v40, v40, v7
	v_mul_f32_e32 v41, v41, v6
	v_mul_f32_e32 v34, v34, v5
	v_mul_f32_e32 v35, v35, v4
	v_mul_f32_e32 v36, v36, v7
	v_mul_f32_e32 v37, v37, v6
	v_mul_f32_e32 v0, v0, v5
	v_mul_f32_e32 v1, v1, v4
	v_mul_f32_e32 v2, v2, v7
	v_mul_f32_e32 v3, v3, v6
	v_mul_f32_e32 v4, v29, v30
	v_mul_f32_e32 v71, v71, v96
	v_mul_f32_e32 v72, v72, v95
	v_mul_f32_e32 v73, v73, v97
	v_mul_f32_e32 v5, v29, v31
	v_mul_f32_e32 v6, v29, v32
	v_mul_f32_e32 v7, v29, v33
	v_mul_f32_e32 v29, v28, v38
	v_mul_f32_e32 v30, v28, v39
	v_mul_f32_e32 v31, v28, v40
	v_mul_f32_e32 v28, v28, v41
	v_mul_f32_e32 v32, v27, v34
	v_mul_f32_e32 v33, v27, v35
	v_mul_f32_e32 v34, v27, v36
	v_mul_f32_e32 v27, v27, v37
	v_mul_f32_e32 v0, v26, v0
	v_mul_f32_e32 v1, v26, v1
	v_mul_f32_e32 v2, v26, v2
	v_mul_f32_e32 v3, v26, v3
	v_mul_f32_e32 v4, v8, v4
	v_mul_f32_e32 v5, v61, v5
	v_mul_f32_e32 v6, v63, v6
	v_mul_f32_e32 v7, v64, v7
	v_mul_f32_e32 v8, v62, v29
	v_mul_f32_e32 v26, v65, v30
	v_mul_f32_e32 v29, v66, v31
	v_mul_f32_e32 v28, v67, v28
	v_mul_f32_e32 v30, v74, v32
	v_mul_f32_e32 v31, v68, v33
	v_mul_f32_e32 v32, v69, v34
	v_mul_f32_e32 v27, v70, v27
	v_mul_f32_e32 v0, v60, v0
	v_mul_f32_e32 v1, v71, v1
	v_mul_f32_e32 v2, v72, v2
	v_mul_f32_e32 v3, v73, v3
	v_cvt_pk_bf16_f32 v4, v4, s0
	v_cvt_pk_bf16_f32 v5, v5, s0
	v_cvt_pk_bf16_f32 v6, v6, s0
	v_cvt_pk_bf16_f32 v7, v7, s0
	v_cvt_pk_bf16_f32 v8, v8, s0
	v_cvt_pk_bf16_f32 v26, v26, s0
	v_cvt_pk_bf16_f32 v29, v29, s0
	v_cvt_pk_bf16_f32 v28, v28, s0
	v_cvt_pk_bf16_f32 v30, v30, s0
	v_cvt_pk_bf16_f32 v31, v31, s0
	v_cvt_pk_bf16_f32 v32, v32, s0
	v_cvt_pk_bf16_f32 v27, v27, s0
	v_cvt_pk_bf16_f32 v0, v0, s0
	v_cvt_pk_bf16_f32 v1, v1, s0
	v_cvt_pk_bf16_f32 v2, v2, s0
	v_cvt_pk_bf16_f32 v3, v3, s0
	global_store_short v12, v4, s[20:21]
	global_store_short v14, v5, s[20:21]
	global_store_short v16, v6, s[20:21]
	global_store_short v18, v7, s[20:21]
	global_store_short v13, v8, s[20:21]
	global_store_short v15, v26, s[20:21]
	global_store_short v17, v29, s[20:21]
	global_store_short v19, v28, s[20:21]
	global_store_short v12, v30, s[100:101]
	global_store_short v14, v31, s[100:101]
	global_store_short v16, v32, s[100:101]
	global_store_short v18, v27, s[100:101]
	global_store_short v13, v0, s[100:101]
	global_store_short v15, v1, s[100:101]
	global_store_short v17, v2, s[100:101]
	global_store_short v19, v3, s[100:101]
	s_cbranch_scc1 .LBB0_1031
	s_cmp_eq_u32 s96, 1
	s_cbranch_scc0 .LBB0_1032
	s_mov_b32 s96, 2
	s_branch .Lp3b_scan
